# combination: setprio around the MFMA section of phase-1 stages + PLE tile streaming + half-tile x loads in K stage 14, on top of the fused phase-5 loop with x loads in stage 14
# speedup vs baseline: 1.0006x; 1.0006x over previous
.Lg1_loop:
	v_add_u32_e32 v136, s11, v100
	ds_read_b128 v[116:119], v136
	v_add_u32_e32 v115, s10, v98
	ds_read_b128 v[120:123], v136 offset:2048
	ds_read_b128 v[124:127], v115
	ds_read_b128 v[128:131], v115 offset:2048
	ds_read_b128 v[132:135], v136 offset:4096
	ds_read_b128 v[136:139], v136 offset:6144
	s_add_u32 s28, s28, 0x80
	s_addc_u32 s29, s29, 0
	s_add_u32 s31, s10, 0xc000
	s_sub_u32 s25, s31, 0x14000
	s_cmp_ge_u32 s31, 0x14000
	s_cselect_b32 s31, s25, s31
	s_add_u32 s31, s31, s30
	s_add_u32 s26, s26, 0x80
	s_addc_u32 s27, s27, 0
	s_add_u32 s24, s10, 0x10000
	s_sub_u32 s25, s24, 0x14000
	s_cmp_ge_u32 s24, 0x14000
	s_cselect_b32 s24, s25, s24
	s_add_u32 s24, s24, s30
	s_mov_b32 m0, s31
	s_nop 0
	global_load_lds_dwordx4 v104, s[28:29]
	s_setprio 1
	s_waitcnt lgkmcnt(3)
	v_mfma_f32_16x16x32_bf16 v[90:93], v[120:123], v[124:127], v[90:93]
	v_mfma_f32_16x16x32_bf16 v[94:97], v[116:119], v[124:127], v[94:97]
	s_waitcnt lgkmcnt(1)
	v_mfma_f32_16x16x32_bf16 v[86:89], v[132:135], v[124:127], v[86:89]
	s_waitcnt lgkmcnt(0)
	v_mfma_f32_16x16x32_bf16 v[82:85], v[136:139], v[124:127], v[82:85]
	s_add_u32 m0, s31, 0x1000
	s_nop 0
	global_load_lds_dwordx4 v105, s[28:29]
	v_mfma_f32_16x16x32_bf16 v[58:61], v[116:119], v[128:131], v[58:61]
	v_mfma_f32_16x16x32_bf16 v[50:53], v[120:123], v[128:131], v[50:53]
	v_mfma_f32_16x16x32_bf16 v[46:49], v[132:135], v[128:131], v[46:49]
	v_mfma_f32_16x16x32_bf16 v[34:37], v[136:139], v[128:131], v[34:37]
	ds_read_b128 v[124:127], v115 offset:4096
	ds_read_b128 v[128:131], v115 offset:6144
	v_add_u32_e32 v140, s11, v101
	s_add_u32 m0, s31, 0x2000
	s_nop 0
	global_load_lds_dwordx4 v106, s[28:29]
	s_waitcnt lgkmcnt(1)
	v_mfma_f32_16x16x32_bf16 v[30:33], v[116:119], v[124:127], v[30:33]
	v_add_u32_e32 v115, s10, v99
	v_mfma_f32_16x16x32_bf16 v[26:29], v[120:123], v[124:127], v[26:29]
	v_mfma_f32_16x16x32_bf16 v[22:25], v[132:135], v[124:127], v[22:25]
	v_mfma_f32_16x16x32_bf16 v[18:21], v[136:139], v[124:127], v[18:21]
	s_add_u32 m0, s31, 0x3000
	s_nop 0
	global_load_lds_dwordx4 v107, s[28:29]
	s_waitcnt lgkmcnt(0)
	v_mfma_f32_16x16x32_bf16 v[14:17], v[116:119], v[128:131], v[14:17]
	ds_read_b128 v[116:119], v140
	v_mfma_f32_16x16x32_bf16 v[10:13], v[120:123], v[128:131], v[10:13]
	v_mfma_f32_16x16x32_bf16 v[6:9], v[132:135], v[128:131], v[6:9]
	v_mfma_f32_16x16x32_bf16 v[2:5], v[136:139], v[128:131], v[2:5]
	ds_read_b128 v[120:123], v140 offset:2048
	ds_read_b128 v[124:127], v115
	ds_read_b128 v[128:131], v115 offset:2048
	ds_read_b128 v[132:135], v140 offset:4096
	ds_read_b128 v[136:139], v140 offset:6144
	s_mov_b32 m0, s24
	s_nop 0
	global_load_lds_dwordx4 v104, s[26:27]
	s_waitcnt lgkmcnt(3)
	v_mfma_f32_16x16x32_bf16 v[94:97], v[116:119], v[124:127], v[94:97]
	v_mfma_f32_16x16x32_bf16 v[90:93], v[120:123], v[124:127], v[90:93]
	s_waitcnt lgkmcnt(1)
	v_mfma_f32_16x16x32_bf16 v[86:89], v[132:135], v[124:127], v[86:89]
	s_waitcnt lgkmcnt(0)
	v_mfma_f32_16x16x32_bf16 v[82:85], v[136:139], v[124:127], v[82:85]
	s_add_u32 m0, s24, 0x1000
	s_nop 0
	global_load_lds_dwordx4 v105, s[26:27]
	v_mfma_f32_16x16x32_bf16 v[58:61], v[116:119], v[128:131], v[58:61]
	v_mfma_f32_16x16x32_bf16 v[50:53], v[120:123], v[128:131], v[50:53]
	v_mfma_f32_16x16x32_bf16 v[46:49], v[132:135], v[128:131], v[46:49]
	v_mfma_f32_16x16x32_bf16 v[34:37], v[136:139], v[128:131], v[34:37]
	ds_read_b128 v[124:127], v115 offset:4096
	ds_read_b128 v[128:131], v115 offset:6144
	s_add_u32 m0, s24, 0x2000
	s_nop 0
	global_load_lds_dwordx4 v106, s[26:27]
	s_waitcnt lgkmcnt(1)
	v_mfma_f32_16x16x32_bf16 v[30:33], v[116:119], v[124:127], v[30:33]
	v_mfma_f32_16x16x32_bf16 v[26:29], v[120:123], v[124:127], v[26:29]
	v_mfma_f32_16x16x32_bf16 v[22:25], v[132:135], v[124:127], v[22:25]
	v_mfma_f32_16x16x32_bf16 v[18:21], v[136:139], v[124:127], v[18:21]
	s_add_u32 m0, s24, 0x3000
	s_nop 0
	global_load_lds_dwordx4 v107, s[26:27]
	s_waitcnt lgkmcnt(0)
	v_mfma_f32_16x16x32_bf16 v[14:17], v[116:119], v[128:131], v[14:17]
	v_mfma_f32_16x16x32_bf16 v[10:13], v[120:123], v[128:131], v[10:13]
	v_mfma_f32_16x16x32_bf16 v[6:9], v[132:135], v[128:131], v[6:9]
	v_mfma_f32_16x16x32_bf16 v[2:5], v[136:139], v[128:131], v[2:5]
	s_add_u32 s10, s10, 0x8000
	s_sub_u32 s25, s10, 0x14000
	s_cmp_ge_u32 s10, 0x14000
	s_cselect_b32 s10, s25, s10
	s_add_u32 s11, s11, 0x8000
	s_sub_u32 s25, s11, 0x14000
	s_cmp_ge_u32 s11, 0x14000
	s_cselect_b32 s11, s25, s11
	s_setprio 0
	s_waitcnt vmcnt(4)
	s_barrier
	s_add_i32 s3, s3, 1
	s_cmp_lg_u32 s3, 14
	s_cbranch_scc1 .Lg1_loop
	s_add_i32 s32, s18, s48
	s_mov_b32 s40, 0
	s_cmp_lt_i32 s32, s12
	s_cbranch_scc0 .Lg1_tail_last
	s_and_b64 vcc, exec, s[50:51]
	s_cbranch_vccz .Lg1_nx_band
	s_mul_hi_i32 s33, s32, 0x92492493
	s_add_i32 s33, s33, s32
	s_lshr_b32 s34, s33, 31
	s_ashr_i32 s33, s33, 4
	s_add_i32 s34, s33, s34
	s_mul_i32 s33, s34, 28
	s_sub_i32 s35, s32, s33
	s_branch .Lg1_nx_done

.Lg1_nx_done:
	s_lshl_b32 s33, s34, 18
	s_add_u32 s36, s54, s33
	s_addc_u32 s37, s55, 0
	s_lshl_b32 s33, s35, 18
	s_add_u32 s38, s54, s33
	s_addc_u32 s39, s55, 0
	s_add_u32 s38, s38, 0xe680000
	s_addc_u32 s39, s39, 0
	s_mov_b32 s40, 1
	v_add_u32_e32 v136, s11, v100
	ds_read_b128 v[116:119], v136
	v_add_u32_e32 v115, s10, v98
	ds_read_b128 v[120:123], v136 offset:2048
	ds_read_b128 v[124:127], v115
	ds_read_b128 v[128:131], v115 offset:2048
	ds_read_b128 v[132:135], v136 offset:4096
	ds_read_b128 v[136:139], v136 offset:6144
	s_add_u32 s28, s28, 0x80
	s_addc_u32 s29, s29, 0
	s_add_u32 s31, s10, 0xc000
	s_sub_u32 s25, s31, 0x14000
	s_cmp_ge_u32 s31, 0x14000
	s_cselect_b32 s31, s25, s31
	s_add_u32 s31, s31, s30
	s_mov_b32 s26, s36
	s_mov_b32 s27, s37
	s_add_u32 s24, s10, 0x10000
	s_sub_u32 s25, s24, 0x14000
	s_cmp_ge_u32 s24, 0x14000
	s_cselect_b32 s24, s25, s24
	s_add_u32 s24, s24, s30
	s_mov_b32 m0, s31
	s_nop 0
	global_load_lds_dwordx4 v104, s[28:29]
	s_setprio 1
	s_waitcnt lgkmcnt(3)
	v_mfma_f32_16x16x32_bf16 v[90:93], v[120:123], v[124:127], v[90:93]
	v_mfma_f32_16x16x32_bf16 v[94:97], v[116:119], v[124:127], v[94:97]
	s_waitcnt lgkmcnt(1)
	v_mfma_f32_16x16x32_bf16 v[86:89], v[132:135], v[124:127], v[86:89]
	s_waitcnt lgkmcnt(0)
	v_mfma_f32_16x16x32_bf16 v[82:85], v[136:139], v[124:127], v[82:85]
	s_add_u32 m0, s31, 0x1000
	s_nop 0
	global_load_lds_dwordx4 v105, s[28:29]
	v_mfma_f32_16x16x32_bf16 v[58:61], v[116:119], v[128:131], v[58:61]
	v_mfma_f32_16x16x32_bf16 v[50:53], v[120:123], v[128:131], v[50:53]
	v_mfma_f32_16x16x32_bf16 v[46:49], v[132:135], v[128:131], v[46:49]
	v_mfma_f32_16x16x32_bf16 v[34:37], v[136:139], v[128:131], v[34:37]
	ds_read_b128 v[124:127], v115 offset:4096
	ds_read_b128 v[128:131], v115 offset:6144
	v_add_u32_e32 v140, s11, v101
	s_add_u32 m0, s31, 0x2000
	s_nop 0
	global_load_lds_dwordx4 v106, s[28:29]
	s_waitcnt lgkmcnt(1)
	v_mfma_f32_16x16x32_bf16 v[30:33], v[116:119], v[124:127], v[30:33]
	v_add_u32_e32 v115, s10, v99
	v_mfma_f32_16x16x32_bf16 v[26:29], v[120:123], v[124:127], v[26:29]
	v_mfma_f32_16x16x32_bf16 v[22:25], v[132:135], v[124:127], v[22:25]
	v_mfma_f32_16x16x32_bf16 v[18:21], v[136:139], v[124:127], v[18:21]
	s_add_u32 m0, s31, 0x3000
	s_nop 0
	global_load_lds_dwordx4 v107, s[28:29]
	s_waitcnt lgkmcnt(0)
	v_mfma_f32_16x16x32_bf16 v[14:17], v[116:119], v[128:131], v[14:17]
	ds_read_b128 v[116:119], v140
	v_mfma_f32_16x16x32_bf16 v[10:13], v[120:123], v[128:131], v[10:13]
	v_mfma_f32_16x16x32_bf16 v[6:9], v[132:135], v[128:131], v[6:9]
	v_mfma_f32_16x16x32_bf16 v[2:5], v[136:139], v[128:131], v[2:5]
	ds_read_b128 v[120:123], v140 offset:2048
	ds_read_b128 v[124:127], v115
	ds_read_b128 v[128:131], v115 offset:2048
	ds_read_b128 v[132:135], v140 offset:4096
	ds_read_b128 v[136:139], v140 offset:6144
	s_mov_b32 m0, s24
	s_nop 0
	global_load_lds_dwordx4 v104, s[26:27]
	s_waitcnt lgkmcnt(3)
	v_mfma_f32_16x16x32_bf16 v[94:97], v[116:119], v[124:127], v[94:97]
	v_mfma_f32_16x16x32_bf16 v[90:93], v[120:123], v[124:127], v[90:93]
	s_waitcnt lgkmcnt(1)
	v_mfma_f32_16x16x32_bf16 v[86:89], v[132:135], v[124:127], v[86:89]
	s_waitcnt lgkmcnt(0)
	v_mfma_f32_16x16x32_bf16 v[82:85], v[136:139], v[124:127], v[82:85]
	s_add_u32 m0, s24, 0x1000
	s_nop 0
	global_load_lds_dwordx4 v105, s[26:27]
	v_mfma_f32_16x16x32_bf16 v[58:61], v[116:119], v[128:131], v[58:61]
	v_mfma_f32_16x16x32_bf16 v[50:53], v[120:123], v[128:131], v[50:53]
	v_mfma_f32_16x16x32_bf16 v[46:49], v[132:135], v[128:131], v[46:49]
	v_mfma_f32_16x16x32_bf16 v[34:37], v[136:139], v[128:131], v[34:37]
	ds_read_b128 v[124:127], v115 offset:4096
	ds_read_b128 v[128:131], v115 offset:6144
	s_add_u32 m0, s24, 0x2000
	s_nop 0
	global_load_lds_dwordx4 v106, s[26:27]
	s_waitcnt lgkmcnt(1)
	v_mfma_f32_16x16x32_bf16 v[30:33], v[116:119], v[124:127], v[30:33]
	v_mfma_f32_16x16x32_bf16 v[26:29], v[120:123], v[124:127], v[26:29]
	v_mfma_f32_16x16x32_bf16 v[22:25], v[132:135], v[124:127], v[22:25]
	v_mfma_f32_16x16x32_bf16 v[18:21], v[136:139], v[124:127], v[18:21]
	s_add_u32 m0, s24, 0x3000
	s_nop 0
	global_load_lds_dwordx4 v107, s[26:27]
	s_waitcnt lgkmcnt(0)
	v_mfma_f32_16x16x32_bf16 v[14:17], v[116:119], v[128:131], v[14:17]
	v_mfma_f32_16x16x32_bf16 v[10:13], v[120:123], v[128:131], v[10:13]
	v_mfma_f32_16x16x32_bf16 v[6:9], v[132:135], v[128:131], v[6:9]
	v_mfma_f32_16x16x32_bf16 v[2:5], v[136:139], v[128:131], v[2:5]
	s_add_u32 s10, s10, 0x8000
	s_sub_u32 s25, s10, 0x14000
	s_cmp_ge_u32 s10, 0x14000
	s_cselect_b32 s10, s25, s10
	s_add_u32 s11, s11, 0x8000
	s_sub_u32 s25, s11, 0x14000
	s_cmp_ge_u32 s11, 0x14000
	s_cselect_b32 s11, s25, s11
	s_setprio 0
	s_waitcnt vmcnt(4)
	s_barrier
	v_add_u32_e32 v136, s11, v100
	ds_read_b128 v[116:119], v136
	v_add_u32_e32 v115, s10, v98
	ds_read_b128 v[120:123], v136 offset:2048
	ds_read_b128 v[124:127], v115
	ds_read_b128 v[128:131], v115 offset:2048
	ds_read_b128 v[132:135], v136 offset:4096
	ds_read_b128 v[136:139], v136 offset:6144
	s_mov_b32 s28, s38
	s_mov_b32 s29, s39
	s_add_u32 s31, s10, 0xc000
	s_sub_u32 s25, s31, 0x14000
	s_cmp_ge_u32 s31, 0x14000
	s_cselect_b32 s31, s25, s31
	s_add_u32 s31, s31, s30
	s_add_u32 s26, s26, 0x80
	s_addc_u32 s27, s27, 0
	s_add_u32 s24, s10, 0x10000
	s_sub_u32 s25, s24, 0x14000
	s_cmp_ge_u32 s24, 0x14000
	s_cselect_b32 s24, s25, s24
	s_add_u32 s24, s24, s30
	s_mov_b32 m0, s31
	s_nop 0
	global_load_lds_dwordx4 v104, s[28:29]
	s_setprio 1
	s_waitcnt lgkmcnt(3)
	v_mfma_f32_16x16x32_bf16 v[90:93], v[120:123], v[124:127], v[90:93]
	v_mfma_f32_16x16x32_bf16 v[94:97], v[116:119], v[124:127], v[94:97]
	s_waitcnt lgkmcnt(1)
	v_mfma_f32_16x16x32_bf16 v[86:89], v[132:135], v[124:127], v[86:89]
	s_waitcnt lgkmcnt(0)
	v_mfma_f32_16x16x32_bf16 v[82:85], v[136:139], v[124:127], v[82:85]
	s_add_u32 m0, s31, 0x1000
	s_nop 0
	global_load_lds_dwordx4 v105, s[28:29]
	v_mfma_f32_16x16x32_bf16 v[58:61], v[116:119], v[128:131], v[58:61]
	v_mfma_f32_16x16x32_bf16 v[50:53], v[120:123], v[128:131], v[50:53]
	v_mfma_f32_16x16x32_bf16 v[46:49], v[132:135], v[128:131], v[46:49]
	v_mfma_f32_16x16x32_bf16 v[34:37], v[136:139], v[128:131], v[34:37]
	ds_read_b128 v[124:127], v115 offset:4096
	ds_read_b128 v[128:131], v115 offset:6144
	v_add_u32_e32 v140, s11, v101
	s_add_u32 m0, s31, 0x2000
	s_nop 0
	global_load_lds_dwordx4 v106, s[28:29]
	s_waitcnt lgkmcnt(1)
	v_mfma_f32_16x16x32_bf16 v[30:33], v[116:119], v[124:127], v[30:33]
	v_add_u32_e32 v115, s10, v99
	v_mfma_f32_16x16x32_bf16 v[26:29], v[120:123], v[124:127], v[26:29]
	v_mfma_f32_16x16x32_bf16 v[22:25], v[132:135], v[124:127], v[22:25]
	v_mfma_f32_16x16x32_bf16 v[18:21], v[136:139], v[124:127], v[18:21]
	s_add_u32 m0, s31, 0x3000
	s_nop 0
	global_load_lds_dwordx4 v107, s[28:29]
	s_waitcnt lgkmcnt(0)
	v_mfma_f32_16x16x32_bf16 v[14:17], v[116:119], v[128:131], v[14:17]
	ds_read_b128 v[116:119], v140
	v_mfma_f32_16x16x32_bf16 v[10:13], v[120:123], v[128:131], v[10:13]
	v_mfma_f32_16x16x32_bf16 v[6:9], v[132:135], v[128:131], v[6:9]
	v_mfma_f32_16x16x32_bf16 v[2:5], v[136:139], v[128:131], v[2:5]
	ds_read_b128 v[120:123], v140 offset:2048
	ds_read_b128 v[124:127], v115
	ds_read_b128 v[128:131], v115 offset:2048
	ds_read_b128 v[132:135], v140 offset:4096
	ds_read_b128 v[136:139], v140 offset:6144
	s_mov_b32 m0, s24
	s_nop 0
	global_load_lds_dwordx4 v104, s[26:27]
	s_waitcnt lgkmcnt(3)
	v_mfma_f32_16x16x32_bf16 v[94:97], v[116:119], v[124:127], v[94:97]
	v_mfma_f32_16x16x32_bf16 v[90:93], v[120:123], v[124:127], v[90:93]
	s_waitcnt lgkmcnt(1)
	v_mfma_f32_16x16x32_bf16 v[86:89], v[132:135], v[124:127], v[86:89]
	s_waitcnt lgkmcnt(0)
	v_mfma_f32_16x16x32_bf16 v[82:85], v[136:139], v[124:127], v[82:85]
	s_add_u32 m0, s24, 0x1000
	s_nop 0
	global_load_lds_dwordx4 v105, s[26:27]
	v_mfma_f32_16x16x32_bf16 v[58:61], v[116:119], v[128:131], v[58:61]
	v_mfma_f32_16x16x32_bf16 v[50:53], v[120:123], v[128:131], v[50:53]
	v_mfma_f32_16x16x32_bf16 v[46:49], v[132:135], v[128:131], v[46:49]
	v_mfma_f32_16x16x32_bf16 v[34:37], v[136:139], v[128:131], v[34:37]
	ds_read_b128 v[124:127], v115 offset:4096
	ds_read_b128 v[128:131], v115 offset:6144
	s_add_u32 m0, s24, 0x2000
	s_nop 0
	global_load_lds_dwordx4 v106, s[26:27]
	s_waitcnt lgkmcnt(1)
	v_mfma_f32_16x16x32_bf16 v[30:33], v[116:119], v[124:127], v[30:33]
	v_mfma_f32_16x16x32_bf16 v[26:29], v[120:123], v[124:127], v[26:29]
	v_mfma_f32_16x16x32_bf16 v[22:25], v[132:135], v[124:127], v[22:25]
	v_mfma_f32_16x16x32_bf16 v[18:21], v[136:139], v[124:127], v[18:21]
	s_add_u32 m0, s24, 0x3000
	s_nop 0
	global_load_lds_dwordx4 v107, s[26:27]
	s_waitcnt lgkmcnt(0)
	v_mfma_f32_16x16x32_bf16 v[14:17], v[116:119], v[128:131], v[14:17]
	v_mfma_f32_16x16x32_bf16 v[10:13], v[120:123], v[128:131], v[10:13]
	v_mfma_f32_16x16x32_bf16 v[6:9], v[132:135], v[128:131], v[6:9]
	v_mfma_f32_16x16x32_bf16 v[2:5], v[136:139], v[128:131], v[2:5]
	s_add_u32 s10, s10, 0x8000
	s_sub_u32 s25, s10, 0x14000
	s_cmp_ge_u32 s10, 0x14000
	s_cselect_b32 s10, s25, s10
	s_add_u32 s11, s11, 0x8000
	s_sub_u32 s25, s11, 0x14000
	s_cmp_ge_u32 s11, 0x14000
	s_cselect_b32 s11, s25, s11
	s_setprio 0
	s_waitcnt vmcnt(4)
	s_barrier
	s_branch .LBB0_114
.Lg1_tail_last:
	v_add_u32_e32 v136, s11, v100
	ds_read_b128 v[116:119], v136
	v_add_u32_e32 v115, s10, v98
	ds_read_b128 v[120:123], v136 offset:2048
	ds_read_b128 v[124:127], v115
	ds_read_b128 v[128:131], v115 offset:2048
	ds_read_b128 v[132:135], v136 offset:4096
	ds_read_b128 v[136:139], v136 offset:6144
	s_add_u32 s28, s28, 0x80
	s_addc_u32 s29, s29, 0
	s_add_u32 s31, s10, 0xc000
	s_sub_u32 s25, s31, 0x14000
	s_cmp_ge_u32 s31, 0x14000
	s_cselect_b32 s31, s25, s31
	s_add_u32 s31, s31, s30
	s_mov_b32 m0, s31
	s_nop 0
	global_load_lds_dwordx4 v104, s[28:29]
	s_setprio 1
	s_waitcnt lgkmcnt(3)
	v_mfma_f32_16x16x32_bf16 v[90:93], v[120:123], v[124:127], v[90:93]
	v_mfma_f32_16x16x32_bf16 v[94:97], v[116:119], v[124:127], v[94:97]
	s_waitcnt lgkmcnt(1)
	v_mfma_f32_16x16x32_bf16 v[86:89], v[132:135], v[124:127], v[86:89]
	s_waitcnt lgkmcnt(0)
	v_mfma_f32_16x16x32_bf16 v[82:85], v[136:139], v[124:127], v[82:85]
	s_add_u32 m0, s31, 0x1000
	s_nop 0
	global_load_lds_dwordx4 v105, s[28:29]
	v_mfma_f32_16x16x32_bf16 v[58:61], v[116:119], v[128:131], v[58:61]
	v_mfma_f32_16x16x32_bf16 v[50:53], v[120:123], v[128:131], v[50:53]
	v_mfma_f32_16x16x32_bf16 v[46:49], v[132:135], v[128:131], v[46:49]
	v_mfma_f32_16x16x32_bf16 v[34:37], v[136:139], v[128:131], v[34:37]
	ds_read_b128 v[124:127], v115 offset:4096
	ds_read_b128 v[128:131], v115 offset:6144
	v_add_u32_e32 v140, s11, v101
	s_add_u32 m0, s31, 0x2000
	s_nop 0
	global_load_lds_dwordx4 v106, s[28:29]
	s_waitcnt lgkmcnt(1)
	v_mfma_f32_16x16x32_bf16 v[30:33], v[116:119], v[124:127], v[30:33]
	v_add_u32_e32 v115, s10, v99
	v_mfma_f32_16x16x32_bf16 v[26:29], v[120:123], v[124:127], v[26:29]
	v_mfma_f32_16x16x32_bf16 v[22:25], v[132:135], v[124:127], v[22:25]
	v_mfma_f32_16x16x32_bf16 v[18:21], v[136:139], v[124:127], v[18:21]
	s_add_u32 m0, s31, 0x3000
	s_nop 0
	global_load_lds_dwordx4 v107, s[28:29]
	s_waitcnt lgkmcnt(0)
	v_mfma_f32_16x16x32_bf16 v[14:17], v[116:119], v[128:131], v[14:17]
	ds_read_b128 v[116:119], v140
	v_mfma_f32_16x16x32_bf16 v[10:13], v[120:123], v[128:131], v[10:13]
	v_mfma_f32_16x16x32_bf16 v[6:9], v[132:135], v[128:131], v[6:9]
	v_mfma_f32_16x16x32_bf16 v[2:5], v[136:139], v[128:131], v[2:5]
	ds_read_b128 v[120:123], v140 offset:2048
	ds_read_b128 v[124:127], v115
	ds_read_b128 v[128:131], v115 offset:2048
	ds_read_b128 v[132:135], v140 offset:4096
	ds_read_b128 v[136:139], v140 offset:6144
	s_waitcnt lgkmcnt(3)
	v_mfma_f32_16x16x32_bf16 v[94:97], v[116:119], v[124:127], v[94:97]
	v_mfma_f32_16x16x32_bf16 v[90:93], v[120:123], v[124:127], v[90:93]
	s_waitcnt lgkmcnt(1)
	v_mfma_f32_16x16x32_bf16 v[86:89], v[132:135], v[124:127], v[86:89]
	s_waitcnt lgkmcnt(0)
	v_mfma_f32_16x16x32_bf16 v[82:85], v[136:139], v[124:127], v[82:85]
	v_mfma_f32_16x16x32_bf16 v[58:61], v[116:119], v[128:131], v[58:61]
	v_mfma_f32_16x16x32_bf16 v[50:53], v[120:123], v[128:131], v[50:53]
	v_mfma_f32_16x16x32_bf16 v[46:49], v[132:135], v[128:131], v[46:49]
	v_mfma_f32_16x16x32_bf16 v[34:37], v[136:139], v[128:131], v[34:37]
	ds_read_b128 v[124:127], v115 offset:4096
	ds_read_b128 v[128:131], v115 offset:6144
	s_waitcnt lgkmcnt(1)
	v_mfma_f32_16x16x32_bf16 v[30:33], v[116:119], v[124:127], v[30:33]
	v_mfma_f32_16x16x32_bf16 v[26:29], v[120:123], v[124:127], v[26:29]
	v_mfma_f32_16x16x32_bf16 v[22:25], v[132:135], v[124:127], v[22:25]
	v_mfma_f32_16x16x32_bf16 v[18:21], v[136:139], v[124:127], v[18:21]
	s_waitcnt lgkmcnt(0)
	v_mfma_f32_16x16x32_bf16 v[14:17], v[116:119], v[128:131], v[14:17]
	v_mfma_f32_16x16x32_bf16 v[10:13], v[120:123], v[128:131], v[10:13]
	v_mfma_f32_16x16x32_bf16 v[6:9], v[132:135], v[128:131], v[6:9]
	v_mfma_f32_16x16x32_bf16 v[2:5], v[136:139], v[128:131], v[2:5]
	s_add_u32 s10, s10, 0x8000
	s_sub_u32 s25, s10, 0x14000
	s_cmp_ge_u32 s10, 0x14000
	s_cselect_b32 s10, s25, s10
	s_add_u32 s11, s11, 0x8000
	s_sub_u32 s25, s11, 0x14000
	s_cmp_ge_u32 s11, 0x14000
	s_cselect_b32 s11, s25, s11
	s_setprio 0
	s_waitcnt vmcnt(0)
	s_barrier
	v_add_u32_e32 v136, s11, v100
	ds_read_b128 v[116:119], v136
	v_add_u32_e32 v115, s10, v98
	ds_read_b128 v[120:123], v136 offset:2048
	ds_read_b128 v[124:127], v115
	ds_read_b128 v[128:131], v115 offset:2048
	ds_read_b128 v[132:135], v136 offset:4096
	ds_read_b128 v[136:139], v136 offset:6144
	s_setprio 1
	s_waitcnt lgkmcnt(3)
	v_mfma_f32_16x16x32_bf16 v[90:93], v[120:123], v[124:127], v[90:93]
	v_mfma_f32_16x16x32_bf16 v[94:97], v[116:119], v[124:127], v[94:97]
	s_waitcnt lgkmcnt(1)
	v_mfma_f32_16x16x32_bf16 v[86:89], v[132:135], v[124:127], v[86:89]
	s_waitcnt lgkmcnt(0)
	v_mfma_f32_16x16x32_bf16 v[82:85], v[136:139], v[124:127], v[82:85]
	v_mfma_f32_16x16x32_bf16 v[58:61], v[116:119], v[128:131], v[58:61]
	v_mfma_f32_16x16x32_bf16 v[50:53], v[120:123], v[128:131], v[50:53]
	v_mfma_f32_16x16x32_bf16 v[46:49], v[132:135], v[128:131], v[46:49]
	v_mfma_f32_16x16x32_bf16 v[34:37], v[136:139], v[128:131], v[34:37]
	ds_read_b128 v[124:127], v115 offset:4096
	ds_read_b128 v[128:131], v115 offset:6144
	v_add_u32_e32 v140, s11, v101
	s_waitcnt lgkmcnt(1)
	v_mfma_f32_16x16x32_bf16 v[30:33], v[116:119], v[124:127], v[30:33]
	v_add_u32_e32 v115, s10, v99
	v_mfma_f32_16x16x32_bf16 v[26:29], v[120:123], v[124:127], v[26:29]
	v_mfma_f32_16x16x32_bf16 v[22:25], v[132:135], v[124:127], v[22:25]
	v_mfma_f32_16x16x32_bf16 v[18:21], v[136:139], v[124:127], v[18:21]
	s_waitcnt lgkmcnt(0)
	v_mfma_f32_16x16x32_bf16 v[14:17], v[116:119], v[128:131], v[14:17]
	ds_read_b128 v[116:119], v140
	v_mfma_f32_16x16x32_bf16 v[10:13], v[120:123], v[128:131], v[10:13]
	v_mfma_f32_16x16x32_bf16 v[6:9], v[132:135], v[128:131], v[6:9]
	v_mfma_f32_16x16x32_bf16 v[2:5], v[136:139], v[128:131], v[2:5]
	ds_read_b128 v[120:123], v140 offset:2048
	ds_read_b128 v[124:127], v115
	ds_read_b128 v[128:131], v115 offset:2048
	ds_read_b128 v[132:135], v140 offset:4096
	ds_read_b128 v[136:139], v140 offset:6144
	s_waitcnt lgkmcnt(3)
	v_mfma_f32_16x16x32_bf16 v[94:97], v[116:119], v[124:127], v[94:97]
	v_mfma_f32_16x16x32_bf16 v[90:93], v[120:123], v[124:127], v[90:93]
	s_waitcnt lgkmcnt(1)
	v_mfma_f32_16x16x32_bf16 v[86:89], v[132:135], v[124:127], v[86:89]
	s_waitcnt lgkmcnt(0)
	v_mfma_f32_16x16x32_bf16 v[82:85], v[136:139], v[124:127], v[82:85]
	v_mfma_f32_16x16x32_bf16 v[58:61], v[116:119], v[128:131], v[58:61]
	v_mfma_f32_16x16x32_bf16 v[50:53], v[120:123], v[128:131], v[50:53]
	v_mfma_f32_16x16x32_bf16 v[46:49], v[132:135], v[128:131], v[46:49]
	v_mfma_f32_16x16x32_bf16 v[34:37], v[136:139], v[128:131], v[34:37]
	ds_read_b128 v[124:127], v115 offset:4096
	ds_read_b128 v[128:131], v115 offset:6144
	s_waitcnt lgkmcnt(1)
	v_mfma_f32_16x16x32_bf16 v[30:33], v[116:119], v[124:127], v[30:33]
	v_mfma_f32_16x16x32_bf16 v[26:29], v[120:123], v[124:127], v[26:29]
	v_mfma_f32_16x16x32_bf16 v[22:25], v[132:135], v[124:127], v[22:25]
	v_mfma_f32_16x16x32_bf16 v[18:21], v[136:139], v[124:127], v[18:21]
	s_waitcnt lgkmcnt(0)
	v_mfma_f32_16x16x32_bf16 v[14:17], v[116:119], v[128:131], v[14:17]
	v_mfma_f32_16x16x32_bf16 v[10:13], v[120:123], v[128:131], v[10:13]
	v_mfma_f32_16x16x32_bf16 v[6:9], v[132:135], v[128:131], v[6:9]
	v_mfma_f32_16x16x32_bf16 v[2:5], v[136:139], v[128:131], v[2:5]
	s_add_u32 s10, s10, 0x8000
	s_sub_u32 s25, s10, 0x14000
	s_cmp_ge_u32 s10, 0x14000
	s_cselect_b32 s10, s25, s10
	s_add_u32 s11, s11, 0x8000
	s_sub_u32 s25, s11, 0x14000
	s_cmp_ge_u32 s11, 0x14000
	s_cselect_b32 s11, s25, s11
	s_setprio 0
	s_waitcnt vmcnt(0)
	s_barrier
	s_branch .LBB0_114
